# gate/up GEMM last round: the 128 leftover tiles are shared row-wise inside each row-block group (both workgroups compute a 128-row half with a dedicated half-tile K loop: no ai=1 MFMAs / fragment read
# speedup vs baseline: 1.0141x; 1.0038x over previous
.LBB0_997:
	s_mov_b64 s[12:13], 0x80
	s_add_i32 m0, s28, 0x18000
	v_lshl_add_u64 v[4:5], v[4:5], 0, s[12:13]
	s_waitcnt vmcnt(2)
	s_barrier
	global_load_lds_dwordx4 v[4:5], off
	v_lshl_add_u64 v[2:3], v[2:3], 0, s[12:13]
	s_add_i32 m0, s28, 0x1a000
	s_add_i32 s34, s28, 0x8000
	s_add_i32 s35, s28, 0xa000
	global_load_lds_dwordx4 v[2:3], off
	v_lshl_add_u64 v[0:1], v[0:1], 0, s[12:13]
	s_mov_b32 m0, s34
	s_add_u32 s14, s10, 0x40080
	global_load_lds_dwordx4 v[0:1], off
	v_lshl_add_u64 v[0:1], v[6:7], 0, s[12:13]
	s_mov_b32 m0, s35
	s_addc_u32 s15, s11, 0
	global_load_lds_dwordx4 v[0:1], off
	s_add_i32 m0, s28, 0x1c000
	v_lshl_add_u64 v[0:1], s[14:15], 0, v[132:133]
	global_load_lds_dwordx4 v[0:1], off
	v_lshl_add_u64 v[0:1], s[14:15], 0, v[128:129]
	s_add_i32 m0, s28, 0x1e000
	s_sext_i32_i16 s1, s4
	global_load_lds_dwordx4 v[0:1], off
	v_and_b32_e32 v0, 15, v10
	v_readlane_b32 s4, v254, 47
	v_and_b32_e32 v4, 48, v10
	v_ashrrev_i32_e32 v2, 6, v10
	v_or_b32_e32 v148, s4, v0
	v_lshlrev_b32_e32 v3, 6, v148
	s_movk_i32 s4, 0x3c0
	v_and_or_b32 v3, v3, s4, v4
	v_readlane_b32 s4, v254, 49
	v_lshl_or_b32 v0, v0, 6, v4
	v_lshlrev_b32_e32 v4, 2, v10
	v_lshl_add_u32 v5, v2, 10, s4
	v_readlane_b32 s4, v254, 60
	v_and_b32_e32 v4, 32, v4
	v_ashrrev_i32_e32 v1, 1, v10
	v_add_lshl_u32 v2, v2, s4, 10
	v_bitop3_b32 v149, v0, v2, v4 bitop3:0xde
	v_lshlrev_b32_e32 v0, 14, v12
	v_and_b32_e32 v1, -8, v1
	v_readlane_b32 s4, v254, 59
	v_and_b32_e32 v0, 0xffff8000, v0
	v_lshl_add_u32 v0, v13, 11, v0
	v_add_u32_e32 v150, s4, v1
	v_and_b32_e32 v1, 1, v12
	v_lshl_or_b32 v0, v1, 6, v0
	v_lshl_add_u32 v136, v14, 1, v0
	v_lshlrev_b32_e32 v0, 14, v8
	v_lshlrev_b32_e32 v6, 2, v148
	v_and_b32_e32 v0, 0xffff8000, v0
	v_and_b32_e32 v6, 32, v6
	s_waitcnt vmcnt(6)
	v_lshl_add_u32 v0, v9, 11, v0
	v_and_b32_e32 v1, 1, v8
	v_bitop3_b32 v3, v3, v5, v6 bitop3:0xde
	v_lshl_or_b32 v0, v1, 6, v0
	s_add_i32 s38, 0, 0x10000
	s_add_i32 s39, 0, 0x14000
	s_ashr_i32 s36, s78, 31
	s_mov_b32 s37, s78
	v_mov_b32_e32 v137, v133
	v_lshl_add_u32 v138, v11, 1, v0
	v_mov_b32_e32 v139, v133
	v_mov_b64_e32 v[140:141], 0x580
	v_mov_b64_e32 v[142:143], 0x57f
	v_add_u32_e32 v151, s38, v149
	v_add_u32_e32 v152, s39, v149
	v_add_u32_e32 v153, 0, v3
	v_mov_b32_e32 v154, 0x358637bd
	s_mov_b32 s40, 0x800000
	s_movk_i32 s41, 0x1600
	s_barrier
	s_mov_b32 s101, 0
	s_branch .LBB0_1000
.Lh9_kloop:
	ds_read_b128 v[144:147], v151
	ds_read_b128 v[156:159], v151 offset:1024
	ds_read_b128 v[160:163], v151 offset:2048
	ds_read_b128 v[164:167], v151 offset:3072
	ds_read_b128 v[168:171], v152
	ds_read_b128 v[172:175], v152 offset:1024
	ds_read_b128 v[176:179], v152 offset:2048
	ds_read_b128 v[180:183], v152 offset:3072
	s_add_u32 s10, s24, 0xfffc0080
	s_addc_u32 s11, s25, -1
	s_cmp_eq_u32 s46, 12
	s_cselect_b32 s21, s17, s11
	s_cselect_b32 s20, s42, s10
	s_cselect_b32 s11, s15, s45
	s_cselect_b32 s10, s43, s44
	v_lshl_add_u64 v[216:217], s[24:25], 0, v[136:137]
	s_add_i32 m0, s28, 0xc000
	ds_read_b128 v[184:187], v153
	ds_read_b128 v[188:191], v153 offset:1024
	ds_read_b128 v[192:195], v153 offset:2048
	ds_read_b128 v[196:199], v153 offset:3072
	ds_read_b128 v[200:203], v153 offset:4096
	ds_read_b128 v[204:207], v153 offset:5120
	ds_read_b128 v[208:211], v153 offset:6144
	ds_read_b128 v[212:215], v153 offset:7168
	v_lshl_add_u64 v[216:217], s[24:25], 0, v[138:139]
	s_add_i32 m0, s28, 0xe000
	s_nop 0
	s_nop 0
	s_waitcnt lgkmcnt(0)
	s_barrier
	s_setprio 1
	s_waitcnt lgkmcnt(0)
	v_mfma_f32_16x16x32_bf16 v[116:119], v[144:147], v[184:187], 0
	v_mfma_f32_16x16x32_bf16 v[112:115], v[160:163], v[184:187], 0
	v_mfma_f32_16x16x32_bf16 v[100:103], v[144:147], v[192:195], 0
	v_mfma_f32_16x16x32_bf16 v[96:99], v[160:163], v[192:195], 0
	v_mfma_f32_16x16x32_bf16 v[84:87], v[144:147], v[200:203], 0
	v_mfma_f32_16x16x32_bf16 v[80:83], v[160:163], v[200:203], 0
	v_mfma_f32_16x16x32_bf16 v[72:75], v[144:147], v[208:211], 0
	v_mfma_f32_16x16x32_bf16 v[64:67], v[160:163], v[208:211], 0
	v_mfma_f32_16x16x32_bf16 v[116:119], v[156:159], v[188:191], v[116:119]
	v_mfma_f32_16x16x32_bf16 v[112:115], v[164:167], v[188:191], v[112:115]
	v_mfma_f32_16x16x32_bf16 v[100:103], v[156:159], v[196:199], v[100:103]
	v_mfma_f32_16x16x32_bf16 v[96:99], v[164:167], v[196:199], v[96:99]
	v_mfma_f32_16x16x32_bf16 v[84:87], v[156:159], v[204:207], v[84:87]
	v_mfma_f32_16x16x32_bf16 v[80:83], v[164:167], v[204:207], v[80:83]
	v_mfma_f32_16x16x32_bf16 v[72:75], v[156:159], v[212:215], v[72:75]
	v_mfma_f32_16x16x32_bf16 v[64:67], v[164:167], v[212:215], v[64:67]
	s_setprio 0
	s_setprio 1
	v_mfma_f32_16x16x32_bf16 v[124:127], v[168:171], v[184:187], 0
	v_mfma_f32_16x16x32_bf16 v[120:123], v[176:179], v[184:187], 0
	v_mfma_f32_16x16x32_bf16 v[108:111], v[168:171], v[192:195], 0
	v_mfma_f32_16x16x32_bf16 v[104:107], v[176:179], v[192:195], 0
	v_mfma_f32_16x16x32_bf16 v[92:95], v[168:171], v[200:203], 0
	v_mfma_f32_16x16x32_bf16 v[88:91], v[176:179], v[200:203], 0
	v_mfma_f32_16x16x32_bf16 v[76:79], v[168:171], v[208:211], 0
	v_mfma_f32_16x16x32_bf16 v[68:71], v[176:179], v[208:211], 0
	v_mfma_f32_16x16x32_bf16 v[124:127], v[172:175], v[188:191], v[124:127]
	v_mfma_f32_16x16x32_bf16 v[120:123], v[180:183], v[188:191], v[120:123]
	v_mfma_f32_16x16x32_bf16 v[108:111], v[172:175], v[196:199], v[108:111]
	v_mfma_f32_16x16x32_bf16 v[104:107], v[180:183], v[196:199], v[104:107]
	v_mfma_f32_16x16x32_bf16 v[92:95], v[172:175], v[204:207], v[92:95]
	v_mfma_f32_16x16x32_bf16 v[88:91], v[180:183], v[204:207], v[88:91]
	v_mfma_f32_16x16x32_bf16 v[76:79], v[172:175], v[212:215], v[76:79]
	v_mfma_f32_16x16x32_bf16 v[68:71], v[180:183], v[212:215], v[68:71]
	s_setprio 0
	s_barrier
	s_add_i32 s47, s38, s50
	v_lshl_add_u64 v[216:217], s[10:11], 0, v[132:133]
	s_mov_b32 m0, s47
	global_load_lds_dwordx4 v[216:217], off
	s_add_i32 m0, s47, 0x2000
	s_add_u32 s48, s10, 0x40000
	v_lshl_add_u64 v[218:219], s[10:11], 0, v[128:129]
	s_addc_u32 s49, s11, 0
	s_add_i32 s47, s39, s50
	global_load_lds_dwordx4 v[218:219], off
	v_lshl_add_u64 v[220:221], s[48:49], 0, v[132:133]
	s_mov_b32 m0, s47
	v_lshl_add_u64 v[222:223], s[20:21], 0, v[130:131]
	global_load_lds_dwordx4 v[220:221], off
	v_lshl_add_u64 v[220:221], s[48:49], 0, v[128:129]
	s_add_i32 m0, s47, 0x2000
	s_nop 0
	global_load_lds_dwordx4 v[220:221], off
	v_lshl_add_u64 v[220:221], s[20:21], 0, v[134:135]
	s_mov_b32 m0, s28
	s_nop 0
	global_load_lds_dwordx4 v[220:221], off
	s_mov_b32 m0, s29
	s_nop 0
	global_load_lds_dwordx4 v[222:223], off
	s_waitcnt vmcnt(6)
	s_waitcnt lgkmcnt(0)
	s_barrier
	s_setprio 1
	s_waitcnt lgkmcnt(0)
	s_setprio 0
	s_setprio 1
	s_setprio 0
	s_barrier
	s_add_i32 s47, 0, 0x18000
	v_add_u32_e32 v155, s47, v149
	s_add_i32 s48, 0, 0x1c000
	ds_read_b128 v[144:147], v155
	ds_read_b128 v[156:159], v155 offset:1024
	ds_read_b128 v[160:163], v155 offset:2048
	ds_read_b128 v[164:167], v155 offset:3072
	v_add_u32_e32 v155, s48, v149
	ds_read_b128 v[168:171], v155
	ds_read_b128 v[172:175], v155 offset:1024
	ds_read_b128 v[176:179], v155 offset:2048
	ds_read_b128 v[180:183], v155 offset:3072
	s_add_u32 s20, s20, 0x40000
	s_addc_u32 s21, s21, 0
	s_mov_b32 m0, s30
	v_lshl_add_u64 v[224:225], s[20:21], 0, v[134:135]
	ds_read_b128 v[184:187], v153 offset:32768
	ds_read_b128 v[188:191], v153 offset:33792
	ds_read_b128 v[192:195], v153 offset:34816
	ds_read_b128 v[196:199], v153 offset:35840
	ds_read_b128 v[200:203], v153 offset:36864
	ds_read_b128 v[204:207], v153 offset:37888
	ds_read_b128 v[208:211], v153 offset:38912
	ds_read_b128 v[212:215], v153 offset:39936
	v_lshl_add_u64 v[224:225], s[20:21], 0, v[130:131]
	s_mov_b32 m0, s31
	s_nop 0
	s_nop 0
	s_waitcnt lgkmcnt(0)
	s_barrier
	s_setprio 1
	s_waitcnt lgkmcnt(0)
	v_mfma_f32_16x16x32_bf16 v[116:119], v[144:147], v[184:187], v[116:119]
	v_mfma_f32_16x16x32_bf16 v[112:115], v[160:163], v[184:187], v[112:115]
	v_mfma_f32_16x16x32_bf16 v[100:103], v[144:147], v[192:195], v[100:103]
	v_mfma_f32_16x16x32_bf16 v[96:99], v[160:163], v[192:195], v[96:99]
	v_mfma_f32_16x16x32_bf16 v[84:87], v[144:147], v[200:203], v[84:87]
	v_mfma_f32_16x16x32_bf16 v[80:83], v[160:163], v[200:203], v[80:83]
	v_mfma_f32_16x16x32_bf16 v[72:75], v[144:147], v[208:211], v[72:75]
	v_mfma_f32_16x16x32_bf16 v[64:67], v[160:163], v[208:211], v[64:67]
	v_mfma_f32_16x16x32_bf16 v[116:119], v[156:159], v[188:191], v[116:119]
	v_mfma_f32_16x16x32_bf16 v[112:115], v[164:167], v[188:191], v[112:115]
	v_mfma_f32_16x16x32_bf16 v[100:103], v[156:159], v[196:199], v[100:103]
	v_mfma_f32_16x16x32_bf16 v[96:99], v[164:167], v[196:199], v[96:99]
	v_mfma_f32_16x16x32_bf16 v[84:87], v[156:159], v[204:207], v[84:87]
	v_mfma_f32_16x16x32_bf16 v[80:83], v[164:167], v[204:207], v[80:83]
	v_mfma_f32_16x16x32_bf16 v[72:75], v[156:159], v[212:215], v[72:75]
	v_mfma_f32_16x16x32_bf16 v[64:67], v[164:167], v[212:215], v[64:67]
	s_setprio 0
	s_setprio 1
	v_mfma_f32_16x16x32_bf16 v[124:127], v[168:171], v[184:187], v[124:127]
	v_mfma_f32_16x16x32_bf16 v[120:123], v[176:179], v[184:187], v[120:123]
	v_mfma_f32_16x16x32_bf16 v[108:111], v[168:171], v[192:195], v[108:111]
	v_mfma_f32_16x16x32_bf16 v[104:107], v[176:179], v[192:195], v[104:107]
	v_mfma_f32_16x16x32_bf16 v[92:95], v[168:171], v[200:203], v[92:95]
	v_mfma_f32_16x16x32_bf16 v[88:91], v[176:179], v[200:203], v[88:91]
	v_mfma_f32_16x16x32_bf16 v[76:79], v[168:171], v[208:211], v[76:79]
	v_mfma_f32_16x16x32_bf16 v[68:71], v[176:179], v[208:211], v[68:71]
	v_mfma_f32_16x16x32_bf16 v[124:127], v[172:175], v[188:191], v[124:127]
	v_mfma_f32_16x16x32_bf16 v[120:123], v[180:183], v[188:191], v[120:123]
	v_mfma_f32_16x16x32_bf16 v[108:111], v[172:175], v[196:199], v[108:111]
	v_mfma_f32_16x16x32_bf16 v[104:107], v[180:183], v[196:199], v[104:107]
	v_mfma_f32_16x16x32_bf16 v[92:95], v[172:175], v[204:207], v[92:95]
	v_mfma_f32_16x16x32_bf16 v[88:91], v[180:183], v[204:207], v[88:91]
	v_mfma_f32_16x16x32_bf16 v[76:79], v[172:175], v[212:215], v[76:79]
	v_mfma_f32_16x16x32_bf16 v[68:71], v[180:183], v[212:215], v[68:71]
	s_setprio 0
	s_barrier
	s_add_i32 s20, s47, s50
	v_lshl_add_u64 v[216:217], v[216:217], 0, s[12:13]
	s_mov_b32 m0, s20
	global_load_lds_dwordx4 v[216:217], off
	s_add_i32 m0, s20, 0x2000
	s_add_u32 s10, s10, 0x40080
	v_lshl_add_u64 v[216:217], v[218:219], 0, s[12:13]
	s_addc_u32 s11, s11, 0
	s_add_i32 s20, s48, s50
	global_load_lds_dwordx4 v[216:217], off
	v_lshl_add_u64 v[216:217], s[10:11], 0, v[132:133]
	s_mov_b32 m0, s20
	s_nop 0
	global_load_lds_dwordx4 v[216:217], off
	v_lshl_add_u64 v[216:217], s[10:11], 0, v[128:129]
	s_add_i32 m0, s20, 0x2000
	s_nop 0
	global_load_lds_dwordx4 v[216:217], off
	v_lshl_add_u64 v[216:217], v[220:221], 0, s[12:13]
	s_mov_b32 m0, s34
	s_nop 0
	global_load_lds_dwordx4 v[216:217], off
	v_lshl_add_u64 v[216:217], v[222:223], 0, s[12:13]
	s_mov_b32 m0, s35
	s_nop 0
	global_load_lds_dwordx4 v[216:217], off
	s_waitcnt vmcnt(6)
	s_waitcnt lgkmcnt(0)
	s_barrier
	s_setprio 1
	s_waitcnt lgkmcnt(0)
	s_setprio 0
	s_setprio 1
	s_setprio 0
	s_barrier
	s_add_i32 s46, s46, 2
	s_add_u32 s24, s24, 0x100
	s_addc_u32 s25, s25, 0
	s_add_u32 s44, s44, 0x100
	s_addc_u32 s45, s45, 0
	s_cmp_gt_u32 s46, 13
.Lh9_loop:
	ds_read_b128 v[144:147], v151
	ds_read_b128 v[156:159], v151 offset:1024
	ds_read_b128 v[160:163], v151 offset:2048
	ds_read_b128 v[164:167], v151 offset:3072
	ds_read_b128 v[168:171], v152
	ds_read_b128 v[172:175], v152 offset:1024
	ds_read_b128 v[176:179], v152 offset:2048
	ds_read_b128 v[180:183], v152 offset:3072
	s_add_u32 s10, s24, 0xfffc0080
	s_addc_u32 s11, s25, -1
	s_cmp_eq_u32 s46, 12
	s_cselect_b32 s21, s17, s11
	s_cselect_b32 s20, s42, s10
	s_cselect_b32 s11, s15, s45
	s_cselect_b32 s10, s43, s44
	v_lshl_add_u64 v[216:217], s[24:25], 0, v[136:137]
	s_add_i32 m0, s28, 0xc000
	ds_read_b128 v[184:187], v153
	ds_read_b128 v[188:191], v153 offset:1024
	ds_read_b128 v[192:195], v153 offset:2048
	ds_read_b128 v[196:199], v153 offset:3072
	ds_read_b128 v[200:203], v153 offset:4096
	ds_read_b128 v[204:207], v153 offset:5120
	ds_read_b128 v[208:211], v153 offset:6144
	ds_read_b128 v[212:215], v153 offset:7168
	v_lshl_add_u64 v[216:217], s[24:25], 0, v[138:139]
	s_add_i32 m0, s28, 0xe000
	s_nop 0
	s_nop 0
	s_waitcnt lgkmcnt(0)
	s_barrier
	s_setprio 1
	s_waitcnt lgkmcnt(0)
	v_mfma_f32_16x16x32_bf16 v[116:119], v[144:147], v[184:187], v[116:119]
	v_mfma_f32_16x16x32_bf16 v[112:115], v[160:163], v[184:187], v[112:115]
	v_mfma_f32_16x16x32_bf16 v[100:103], v[144:147], v[192:195], v[100:103]
	v_mfma_f32_16x16x32_bf16 v[96:99], v[160:163], v[192:195], v[96:99]
	v_mfma_f32_16x16x32_bf16 v[84:87], v[144:147], v[200:203], v[84:87]
	v_mfma_f32_16x16x32_bf16 v[80:83], v[160:163], v[200:203], v[80:83]
	v_mfma_f32_16x16x32_bf16 v[72:75], v[144:147], v[208:211], v[72:75]
	v_mfma_f32_16x16x32_bf16 v[64:67], v[160:163], v[208:211], v[64:67]
	v_mfma_f32_16x16x32_bf16 v[116:119], v[156:159], v[188:191], v[116:119]
	v_mfma_f32_16x16x32_bf16 v[112:115], v[164:167], v[188:191], v[112:115]
	v_mfma_f32_16x16x32_bf16 v[100:103], v[156:159], v[196:199], v[100:103]
	v_mfma_f32_16x16x32_bf16 v[96:99], v[164:167], v[196:199], v[96:99]
	v_mfma_f32_16x16x32_bf16 v[84:87], v[156:159], v[204:207], v[84:87]
	v_mfma_f32_16x16x32_bf16 v[80:83], v[164:167], v[204:207], v[80:83]
	v_mfma_f32_16x16x32_bf16 v[72:75], v[156:159], v[212:215], v[72:75]
	v_mfma_f32_16x16x32_bf16 v[64:67], v[164:167], v[212:215], v[64:67]
	s_setprio 0
	s_setprio 1
	v_mfma_f32_16x16x32_bf16 v[124:127], v[168:171], v[184:187], v[124:127]
	v_mfma_f32_16x16x32_bf16 v[120:123], v[176:179], v[184:187], v[120:123]
	v_mfma_f32_16x16x32_bf16 v[108:111], v[168:171], v[192:195], v[108:111]
	v_mfma_f32_16x16x32_bf16 v[104:107], v[176:179], v[192:195], v[104:107]
	v_mfma_f32_16x16x32_bf16 v[92:95], v[168:171], v[200:203], v[92:95]
	v_mfma_f32_16x16x32_bf16 v[88:91], v[176:179], v[200:203], v[88:91]
	v_mfma_f32_16x16x32_bf16 v[76:79], v[168:171], v[208:211], v[76:79]
	v_mfma_f32_16x16x32_bf16 v[68:71], v[176:179], v[208:211], v[68:71]
	v_mfma_f32_16x16x32_bf16 v[124:127], v[172:175], v[188:191], v[124:127]
	v_mfma_f32_16x16x32_bf16 v[120:123], v[180:183], v[188:191], v[120:123]
	v_mfma_f32_16x16x32_bf16 v[108:111], v[172:175], v[196:199], v[108:111]
	v_mfma_f32_16x16x32_bf16 v[104:107], v[180:183], v[196:199], v[104:107]
	v_mfma_f32_16x16x32_bf16 v[92:95], v[172:175], v[204:207], v[92:95]
	v_mfma_f32_16x16x32_bf16 v[88:91], v[180:183], v[204:207], v[88:91]
	v_mfma_f32_16x16x32_bf16 v[76:79], v[172:175], v[212:215], v[76:79]
	v_mfma_f32_16x16x32_bf16 v[68:71], v[180:183], v[212:215], v[68:71]
	s_setprio 0
	s_barrier
	s_add_i32 s47, s38, s50
	v_lshl_add_u64 v[216:217], s[10:11], 0, v[132:133]
	s_mov_b32 m0, s47
	global_load_lds_dwordx4 v[216:217], off
	s_add_i32 m0, s47, 0x2000
	s_add_u32 s48, s10, 0x40000
	v_lshl_add_u64 v[218:219], s[10:11], 0, v[128:129]
	s_addc_u32 s49, s11, 0
	s_add_i32 s47, s39, s50
	global_load_lds_dwordx4 v[218:219], off
	v_lshl_add_u64 v[220:221], s[48:49], 0, v[132:133]
	s_mov_b32 m0, s47
	v_lshl_add_u64 v[222:223], s[20:21], 0, v[130:131]
	global_load_lds_dwordx4 v[220:221], off
	v_lshl_add_u64 v[220:221], s[48:49], 0, v[128:129]
	s_add_i32 m0, s47, 0x2000
	s_nop 0
	global_load_lds_dwordx4 v[220:221], off
	v_lshl_add_u64 v[220:221], s[20:21], 0, v[134:135]
	s_mov_b32 m0, s28
	s_nop 0
	global_load_lds_dwordx4 v[220:221], off
	s_mov_b32 m0, s29
	s_nop 0
	global_load_lds_dwordx4 v[222:223], off
	s_waitcnt vmcnt(6)
	s_waitcnt lgkmcnt(0)
	s_barrier
	s_setprio 1
	s_waitcnt lgkmcnt(0)
	s_setprio 0
	s_setprio 1
	s_setprio 0
	s_barrier
	s_add_i32 s47, 0, 0x18000
	v_add_u32_e32 v155, s47, v149
	s_add_i32 s48, 0, 0x1c000
	ds_read_b128 v[144:147], v155
	ds_read_b128 v[156:159], v155 offset:1024
	ds_read_b128 v[160:163], v155 offset:2048
	ds_read_b128 v[164:167], v155 offset:3072
	v_add_u32_e32 v155, s48, v149
	ds_read_b128 v[168:171], v155
	ds_read_b128 v[172:175], v155 offset:1024
	ds_read_b128 v[176:179], v155 offset:2048
	ds_read_b128 v[180:183], v155 offset:3072
	s_add_u32 s20, s20, 0x40000
	s_addc_u32 s21, s21, 0
	s_mov_b32 m0, s30
	v_lshl_add_u64 v[224:225], s[20:21], 0, v[134:135]
	ds_read_b128 v[184:187], v153 offset:32768
	ds_read_b128 v[188:191], v153 offset:33792
	ds_read_b128 v[192:195], v153 offset:34816
	ds_read_b128 v[196:199], v153 offset:35840
	ds_read_b128 v[200:203], v153 offset:36864
	ds_read_b128 v[204:207], v153 offset:37888
	ds_read_b128 v[208:211], v153 offset:38912
	ds_read_b128 v[212:215], v153 offset:39936
	v_lshl_add_u64 v[224:225], s[20:21], 0, v[130:131]
	s_mov_b32 m0, s31
	s_nop 0
	s_nop 0
	s_waitcnt lgkmcnt(0)
	s_barrier
	s_setprio 1
	s_waitcnt lgkmcnt(0)
	v_mfma_f32_16x16x32_bf16 v[116:119], v[144:147], v[184:187], v[116:119]
	v_mfma_f32_16x16x32_bf16 v[112:115], v[160:163], v[184:187], v[112:115]
	v_mfma_f32_16x16x32_bf16 v[100:103], v[144:147], v[192:195], v[100:103]
	v_mfma_f32_16x16x32_bf16 v[96:99], v[160:163], v[192:195], v[96:99]
	v_mfma_f32_16x16x32_bf16 v[84:87], v[144:147], v[200:203], v[84:87]
	v_mfma_f32_16x16x32_bf16 v[80:83], v[160:163], v[200:203], v[80:83]
	v_mfma_f32_16x16x32_bf16 v[72:75], v[144:147], v[208:211], v[72:75]
	v_mfma_f32_16x16x32_bf16 v[64:67], v[160:163], v[208:211], v[64:67]
	v_mfma_f32_16x16x32_bf16 v[116:119], v[156:159], v[188:191], v[116:119]
	v_mfma_f32_16x16x32_bf16 v[112:115], v[164:167], v[188:191], v[112:115]
	v_mfma_f32_16x16x32_bf16 v[100:103], v[156:159], v[196:199], v[100:103]
	v_mfma_f32_16x16x32_bf16 v[96:99], v[164:167], v[196:199], v[96:99]
	v_mfma_f32_16x16x32_bf16 v[84:87], v[156:159], v[204:207], v[84:87]
	v_mfma_f32_16x16x32_bf16 v[80:83], v[164:167], v[204:207], v[80:83]
	v_mfma_f32_16x16x32_bf16 v[72:75], v[156:159], v[212:215], v[72:75]
	v_mfma_f32_16x16x32_bf16 v[64:67], v[164:167], v[212:215], v[64:67]
	s_setprio 0
	s_setprio 1
	v_mfma_f32_16x16x32_bf16 v[124:127], v[168:171], v[184:187], v[124:127]
	v_mfma_f32_16x16x32_bf16 v[120:123], v[176:179], v[184:187], v[120:123]
	v_mfma_f32_16x16x32_bf16 v[108:111], v[168:171], v[192:195], v[108:111]
	v_mfma_f32_16x16x32_bf16 v[104:107], v[176:179], v[192:195], v[104:107]
	v_mfma_f32_16x16x32_bf16 v[92:95], v[168:171], v[200:203], v[92:95]
	v_mfma_f32_16x16x32_bf16 v[88:91], v[176:179], v[200:203], v[88:91]
	v_mfma_f32_16x16x32_bf16 v[76:79], v[168:171], v[208:211], v[76:79]
	v_mfma_f32_16x16x32_bf16 v[68:71], v[176:179], v[208:211], v[68:71]
	v_mfma_f32_16x16x32_bf16 v[124:127], v[172:175], v[188:191], v[124:127]
	v_mfma_f32_16x16x32_bf16 v[120:123], v[180:183], v[188:191], v[120:123]
	v_mfma_f32_16x16x32_bf16 v[108:111], v[172:175], v[196:199], v[108:111]
	v_mfma_f32_16x16x32_bf16 v[104:107], v[180:183], v[196:199], v[104:107]
	v_mfma_f32_16x16x32_bf16 v[92:95], v[172:175], v[204:207], v[92:95]
	v_mfma_f32_16x16x32_bf16 v[88:91], v[180:183], v[204:207], v[88:91]
	v_mfma_f32_16x16x32_bf16 v[76:79], v[172:175], v[212:215], v[76:79]
	v_mfma_f32_16x16x32_bf16 v[68:71], v[180:183], v[212:215], v[68:71]
	s_setprio 0
	s_barrier
	s_add_i32 s20, s47, s50
	v_lshl_add_u64 v[216:217], v[216:217], 0, s[12:13]
	s_mov_b32 m0, s20
	global_load_lds_dwordx4 v[216:217], off
	s_add_i32 m0, s20, 0x2000
	s_add_u32 s10, s10, 0x40080
	v_lshl_add_u64 v[216:217], v[218:219], 0, s[12:13]
	s_addc_u32 s11, s11, 0
	s_add_i32 s20, s48, s50
	global_load_lds_dwordx4 v[216:217], off
	v_lshl_add_u64 v[216:217], s[10:11], 0, v[132:133]
	s_mov_b32 m0, s20
	s_nop 0
	global_load_lds_dwordx4 v[216:217], off
	v_lshl_add_u64 v[216:217], s[10:11], 0, v[128:129]
	s_add_i32 m0, s20, 0x2000
	s_nop 0
	global_load_lds_dwordx4 v[216:217], off
	v_lshl_add_u64 v[216:217], v[220:221], 0, s[12:13]
	s_mov_b32 m0, s34
	s_nop 0
	global_load_lds_dwordx4 v[216:217], off
	v_lshl_add_u64 v[216:217], v[222:223], 0, s[12:13]
	s_mov_b32 m0, s35
	s_nop 0
	global_load_lds_dwordx4 v[216:217], off
	s_waitcnt vmcnt(6)
	s_waitcnt lgkmcnt(0)
	s_barrier
	s_setprio 1
	s_waitcnt lgkmcnt(0)
	s_setprio 0
	s_setprio 1
	s_setprio 0
	s_barrier
	s_add_i32 s46, s46, 2
	s_add_u32 s24, s24, 0x100
	s_addc_u32 s25, s25, 0
	s_add_u32 s44, s44, 0x100
	s_addc_u32 s45, s45, 0
	s_cmp_gt_u32 s46, 13
	s_cbranch_scc0 .Lh9_loop
	s_branch .Lh9_after

.LBB0_999:
	s_andn2_b64 vcc, exec, s[0:1]
	s_mov_b32 s1, s14
	s_mov_b32 s0, s16
	s_mov_b64 s[10:11], s[22:23]
	s_mov_b64 s[20:21], s[18:19]
	s_lshr_b32 s101, s101, 4
	s_cbranch_vccz .LBB0_1009
.LBB0_1000:
	s_add_i32 s33, s33, 1
	s_mul_i32 s4, s33, s36
	s_mul_hi_u32 s5, s33, s37
	s_add_i32 s5, s5, s4
	s_mul_i32 s4, s33, s37
	s_add_u32 s18, s4, s70
	s_addc_u32 s19, s5, s26
	v_cmp_gt_i64_e32 vcc, s[18:19], v[142:143]
	v_cmp_lt_i64_e64 s[4:5], s[18:19], v[140:141]
	s_and_b32 s101, s101, 3
	s_cmp_eq_u32 s33, 5
	s_cbranch_scc0 .Lh9_nomode
	s_cmp_lg_u32 s98, 0
	s_cbranch_scc0 .Lh9_nomode
	s_or_b32 s101, s101, 0x10
	s_cmp_lt_u32 s70, 0x80
	s_cbranch_scc1 .Lh9_nomode
	s_or_b32 s101, s101, 0x20
	s_mov_b64 s[4:5], exec
	s_lshr_b32 s14, s70, 6
	s_and_b32 s14, s14, 1
	s_add_i32 s14, s14, 20
	s_mov_b32 s16, s0
	s_branch .LBB0_1002
.Lh9_nomode:
	s_cbranch_vccnz .LBB0_1002
	s_ashr_i32 s14, s18, 31
	s_lshr_b32 s14, s14, 29
	s_add_i32 s14, s18, s14
	s_ashr_i32 s15, s14, 3
	s_and_b32 s14, s14, -8
	s_sub_i32 s14, s18, s14
	s_cmp_lt_i32 s14, 0
	s_cselect_b32 s16, s27, 0xb0
	s_mul_i32 s14, s14, s16
	s_add_i32 s14, s14, s15
	s_mul_hi_i32 s15, s14, 0x2e8ba2e9
	s_lshr_b32 s16, s15, 31
	s_ashr_i32 s15, s15, 5
	s_add_i32 s15, s15, s16
	s_lshl_b32 s16, s15, 3
	s_sub_i32 s17, 64, s16
	s_min_i32 s17, s17, 8
	s_abs_i32 s18, s17
	v_cvt_f32_u32_e32 v0, s18
	s_sub_i32 s22, 0, s18
	s_mulk_i32 s15, 0xb0
	s_sub_i32 s15, s14, s15
	v_rcp_iflag_f32_e32 v0, v0
	s_abs_i32 s14, s15
	s_xor_b32 s19, s15, s17
	s_ashr_i32 s19, s19, 31
	v_mul_f32_e32 v0, 0x4f7ffffe, v0
	v_cvt_u32_f32_e32 v0, v0
	s_nop 0
	v_readfirstlane_b32 s23, v0
	s_mul_i32 s22, s22, s23
	s_mul_hi_u32 s22, s23, s22
	s_add_i32 s23, s23, s22
	s_mul_hi_u32 s22, s14, s23
	s_mul_i32 s23, s22, s18
	s_sub_i32 s14, s14, s23
	s_add_i32 s24, s22, 1
	s_sub_i32 s23, s14, s18
	s_cmp_ge_u32 s14, s18
	s_cselect_b32 s22, s24, s22
	s_cselect_b32 s14, s23, s14
	s_add_i32 s23, s22, 1
	s_cmp_ge_u32 s14, s18
	s_cselect_b32 s14, s23, s22
	s_xor_b32 s14, s14, s19
	s_sub_i32 s14, s14, s19
	s_mul_i32 s17, s14, s17
	s_sub_i32 s15, s15, s17
	s_add_i32 s16, s16, s15
.LBB0_1002:
	s_ashr_i32 s17, s16, 31
	s_lshl_b64 s[18:19], s[16:17], 19
	s_add_u32 s18, s52, s18
	s_addc_u32 s19, s53, s19
	s_bfe_u32 s99, s101, 0x10005
	s_lshl_b32 s99, s99, 18
	s_add_u32 s18, s18, s99
	s_addc_u32 s19, s19, 0
	s_and_b64 s[22:23], s[4:5], exec
	s_cselect_b32 s17, s19, s21
	s_cselect_b32 s42, s18, s20
	s_ashr_i32 s15, s14, 31
	s_lshl_b64 s[22:23], s[14:15], 19
	s_add_u32 s22, s2, s22
	s_addc_u32 s23, s3, s23
	s_and_b64 s[24:25], s[4:5], exec
	s_cselect_b32 s15, s23, s11
	s_cselect_b32 s43, s22, s10
	s_add_u32 s24, s20, 0x40080
	s_addc_u32 s25, s21, 0
	s_add_u32 s44, s10, 0x100
	s_nop 7
	s_nop 7
	s_addc_u32 s45, s11, 0
	s_mov_b32 s46, -2
	v_readlane_b32 s50, v254, 54
	s_bitcmp1_b32 s101, 0
	s_cbranch_scc1 .Lh9_kloop
	ds_read_b128 v[144:147], v151
	ds_read_b128 v[156:159], v151 offset:1024
	ds_read_b128 v[160:163], v151 offset:2048
	ds_read_b128 v[164:167], v151 offset:3072
	ds_read_b128 v[168:171], v152
	ds_read_b128 v[172:175], v152 offset:1024
	ds_read_b128 v[176:179], v152 offset:2048
	ds_read_b128 v[180:183], v152 offset:3072
	s_add_u32 s10, s24, 0xfffc0080
	s_addc_u32 s11, s25, -1
	s_cmp_eq_u32 s46, 12
	s_cselect_b32 s21, s17, s11
	s_cselect_b32 s20, s42, s10
	s_cselect_b32 s11, s15, s45
	s_cselect_b32 s10, s43, s44
	v_lshl_add_u64 v[216:217], s[24:25], 0, v[136:137]
	s_add_i32 m0, s28, 0xc000
	ds_read_b128 v[184:187], v153
	ds_read_b128 v[188:191], v153 offset:1024
	ds_read_b128 v[192:195], v153 offset:2048
	ds_read_b128 v[196:199], v153 offset:3072
	ds_read_b128 v[200:203], v153 offset:4096
	ds_read_b128 v[204:207], v153 offset:5120
	ds_read_b128 v[208:211], v153 offset:6144
	ds_read_b128 v[212:215], v153 offset:7168
	global_load_lds_dwordx4 v[216:217], off
	v_lshl_add_u64 v[216:217], s[24:25], 0, v[138:139]
	s_add_i32 m0, s28, 0xe000
	s_nop 0
	global_load_lds_dwordx4 v[216:217], off
	s_waitcnt vmcnt(8)
	s_waitcnt lgkmcnt(0)
	s_barrier
	s_setprio 1
	s_waitcnt lgkmcnt(0)
	v_mfma_f32_16x16x32_bf16 v[116:119], v[144:147], v[184:187], 0
	v_mfma_f32_16x16x32_bf16 v[112:115], v[160:163], v[184:187], 0
	v_mfma_f32_16x16x32_bf16 v[100:103], v[144:147], v[192:195], 0
	v_mfma_f32_16x16x32_bf16 v[96:99], v[160:163], v[192:195], 0
	v_mfma_f32_16x16x32_bf16 v[84:87], v[144:147], v[200:203], 0
	v_mfma_f32_16x16x32_bf16 v[80:83], v[160:163], v[200:203], 0
	v_mfma_f32_16x16x32_bf16 v[72:75], v[144:147], v[208:211], 0
	v_mfma_f32_16x16x32_bf16 v[64:67], v[160:163], v[208:211], 0
	v_mfma_f32_16x16x32_bf16 v[116:119], v[156:159], v[188:191], v[116:119]
	v_mfma_f32_16x16x32_bf16 v[112:115], v[164:167], v[188:191], v[112:115]
	v_mfma_f32_16x16x32_bf16 v[100:103], v[156:159], v[196:199], v[100:103]
	v_mfma_f32_16x16x32_bf16 v[96:99], v[164:167], v[196:199], v[96:99]
	v_mfma_f32_16x16x32_bf16 v[84:87], v[156:159], v[204:207], v[84:87]
	v_mfma_f32_16x16x32_bf16 v[80:83], v[164:167], v[204:207], v[80:83]
	v_mfma_f32_16x16x32_bf16 v[72:75], v[156:159], v[212:215], v[72:75]
	v_mfma_f32_16x16x32_bf16 v[64:67], v[164:167], v[212:215], v[64:67]
	s_setprio 0
	s_setprio 1
	v_mfma_f32_16x16x32_bf16 v[124:127], v[168:171], v[184:187], 0
	v_mfma_f32_16x16x32_bf16 v[120:123], v[176:179], v[184:187], 0
	v_mfma_f32_16x16x32_bf16 v[108:111], v[168:171], v[192:195], 0
	v_mfma_f32_16x16x32_bf16 v[104:107], v[176:179], v[192:195], 0
	v_mfma_f32_16x16x32_bf16 v[92:95], v[168:171], v[200:203], 0
	v_mfma_f32_16x16x32_bf16 v[88:91], v[176:179], v[200:203], 0
	v_mfma_f32_16x16x32_bf16 v[76:79], v[168:171], v[208:211], 0
	v_mfma_f32_16x16x32_bf16 v[68:71], v[176:179], v[208:211], 0
	v_mfma_f32_16x16x32_bf16 v[124:127], v[172:175], v[188:191], v[124:127]
	v_mfma_f32_16x16x32_bf16 v[120:123], v[180:183], v[188:191], v[120:123]
	v_mfma_f32_16x16x32_bf16 v[108:111], v[172:175], v[196:199], v[108:111]
	v_mfma_f32_16x16x32_bf16 v[104:107], v[180:183], v[196:199], v[104:107]
	v_mfma_f32_16x16x32_bf16 v[92:95], v[172:175], v[204:207], v[92:95]
	v_mfma_f32_16x16x32_bf16 v[88:91], v[180:183], v[204:207], v[88:91]
	v_mfma_f32_16x16x32_bf16 v[76:79], v[172:175], v[212:215], v[76:79]
	v_mfma_f32_16x16x32_bf16 v[68:71], v[180:183], v[212:215], v[68:71]
	s_setprio 0
	s_barrier
	s_add_i32 s47, s38, s50
	v_lshl_add_u64 v[216:217], s[10:11], 0, v[132:133]
	s_mov_b32 m0, s47
	ds_read_b128 v[184:187], v153 offset:16384
	ds_read_b128 v[188:191], v153 offset:17408
	ds_read_b128 v[192:195], v153 offset:18432
	ds_read_b128 v[196:199], v153 offset:19456
	ds_read_b128 v[200:203], v153 offset:20480
	ds_read_b128 v[204:207], v153 offset:21504
	ds_read_b128 v[208:211], v153 offset:22528
	ds_read_b128 v[212:215], v153 offset:23552
	global_load_lds_dwordx4 v[216:217], off
	s_add_i32 m0, s47, 0x2000
	s_add_u32 s48, s10, 0x40000
	v_lshl_add_u64 v[218:219], s[10:11], 0, v[128:129]
	s_addc_u32 s49, s11, 0
	s_add_i32 s47, s39, s50
	global_load_lds_dwordx4 v[218:219], off
	v_lshl_add_u64 v[220:221], s[48:49], 0, v[132:133]
	s_mov_b32 m0, s47
	v_lshl_add_u64 v[222:223], s[20:21], 0, v[130:131]
	global_load_lds_dwordx4 v[220:221], off
	v_lshl_add_u64 v[220:221], s[48:49], 0, v[128:129]
	s_add_i32 m0, s47, 0x2000
	s_nop 0
	global_load_lds_dwordx4 v[220:221], off
	v_lshl_add_u64 v[220:221], s[20:21], 0, v[134:135]
	s_mov_b32 m0, s28
	s_nop 0
	global_load_lds_dwordx4 v[220:221], off
	s_mov_b32 m0, s29
	s_nop 0
	global_load_lds_dwordx4 v[222:223], off
	s_waitcnt vmcnt(8)
	s_waitcnt lgkmcnt(0)
	s_barrier
	s_setprio 1
	s_waitcnt lgkmcnt(0)
	v_mfma_f32_16x16x32_bf16 v[56:59], v[144:147], v[184:187], 0
	v_mfma_f32_16x16x32_bf16 v[48:51], v[160:163], v[184:187], 0
	v_mfma_f32_16x16x32_bf16 v[40:43], v[144:147], v[192:195], 0
	v_mfma_f32_16x16x32_bf16 v[32:35], v[160:163], v[192:195], 0
	v_mfma_f32_16x16x32_bf16 v[24:27], v[144:147], v[200:203], 0
	v_mfma_f32_16x16x32_bf16 v[16:19], v[160:163], v[200:203], 0
	v_mfma_f32_16x16x32_bf16 v[8:11], v[144:147], v[208:211], 0
	v_mfma_f32_16x16x32_bf16 v[0:3], v[160:163], v[208:211], 0
	v_mfma_f32_16x16x32_bf16 v[56:59], v[156:159], v[188:191], v[56:59]
	v_mfma_f32_16x16x32_bf16 v[48:51], v[164:167], v[188:191], v[48:51]
	v_mfma_f32_16x16x32_bf16 v[40:43], v[156:159], v[196:199], v[40:43]
	v_mfma_f32_16x16x32_bf16 v[32:35], v[164:167], v[196:199], v[32:35]
	v_mfma_f32_16x16x32_bf16 v[24:27], v[156:159], v[204:207], v[24:27]
	v_mfma_f32_16x16x32_bf16 v[16:19], v[164:167], v[204:207], v[16:19]
	v_mfma_f32_16x16x32_bf16 v[8:11], v[156:159], v[212:215], v[8:11]
	v_mfma_f32_16x16x32_bf16 v[0:3], v[164:167], v[212:215], v[0:3]
	s_setprio 0
	s_setprio 1
	v_mfma_f32_16x16x32_bf16 v[60:63], v[168:171], v[184:187], 0
	v_mfma_f32_16x16x32_bf16 v[52:55], v[176:179], v[184:187], 0
	v_mfma_f32_16x16x32_bf16 v[44:47], v[168:171], v[192:195], 0
	v_mfma_f32_16x16x32_bf16 v[36:39], v[176:179], v[192:195], 0
	v_mfma_f32_16x16x32_bf16 v[28:31], v[168:171], v[200:203], 0
	v_mfma_f32_16x16x32_bf16 v[20:23], v[176:179], v[200:203], 0
	v_mfma_f32_16x16x32_bf16 v[12:15], v[168:171], v[208:211], 0
	v_mfma_f32_16x16x32_bf16 v[4:7], v[176:179], v[208:211], 0
	v_mfma_f32_16x16x32_bf16 v[60:63], v[172:175], v[188:191], v[60:63]
	v_mfma_f32_16x16x32_bf16 v[52:55], v[180:183], v[188:191], v[52:55]
	v_mfma_f32_16x16x32_bf16 v[44:47], v[172:175], v[196:199], v[44:47]
	v_mfma_f32_16x16x32_bf16 v[36:39], v[180:183], v[196:199], v[36:39]
	v_mfma_f32_16x16x32_bf16 v[28:31], v[172:175], v[204:207], v[28:31]
	v_mfma_f32_16x16x32_bf16 v[20:23], v[180:183], v[204:207], v[20:23]
	v_mfma_f32_16x16x32_bf16 v[12:15], v[172:175], v[212:215], v[12:15]
	v_mfma_f32_16x16x32_bf16 v[4:7], v[180:183], v[212:215], v[4:7]
	s_setprio 0
	s_barrier
	s_add_i32 s47, 0, 0x18000
	v_add_u32_e32 v155, s47, v149
	s_add_i32 s48, 0, 0x1c000
	ds_read_b128 v[144:147], v155
	ds_read_b128 v[156:159], v155 offset:1024
	ds_read_b128 v[160:163], v155 offset:2048
	ds_read_b128 v[164:167], v155 offset:3072
	v_add_u32_e32 v155, s48, v149
	ds_read_b128 v[168:171], v155
	ds_read_b128 v[172:175], v155 offset:1024
	ds_read_b128 v[176:179], v155 offset:2048
	ds_read_b128 v[180:183], v155 offset:3072
	s_add_u32 s20, s20, 0x40000
	s_addc_u32 s21, s21, 0
	s_mov_b32 m0, s30
	v_lshl_add_u64 v[224:225], s[20:21], 0, v[134:135]
	ds_read_b128 v[184:187], v153 offset:32768
	ds_read_b128 v[188:191], v153 offset:33792
	ds_read_b128 v[192:195], v153 offset:34816
	ds_read_b128 v[196:199], v153 offset:35840
	ds_read_b128 v[200:203], v153 offset:36864
	ds_read_b128 v[204:207], v153 offset:37888
	ds_read_b128 v[208:211], v153 offset:38912
	ds_read_b128 v[212:215], v153 offset:39936
	global_load_lds_dwordx4 v[224:225], off
	v_lshl_add_u64 v[224:225], s[20:21], 0, v[130:131]
	s_mov_b32 m0, s31
	s_nop 0
	global_load_lds_dwordx4 v[224:225], off
	s_waitcnt vmcnt(8)
	s_waitcnt lgkmcnt(0)
	s_barrier
	s_setprio 1
	s_waitcnt lgkmcnt(0)
	v_mfma_f32_16x16x32_bf16 v[116:119], v[144:147], v[184:187], v[116:119]
	v_mfma_f32_16x16x32_bf16 v[112:115], v[160:163], v[184:187], v[112:115]
	v_mfma_f32_16x16x32_bf16 v[100:103], v[144:147], v[192:195], v[100:103]
	v_mfma_f32_16x16x32_bf16 v[96:99], v[160:163], v[192:195], v[96:99]
	v_mfma_f32_16x16x32_bf16 v[84:87], v[144:147], v[200:203], v[84:87]
	v_mfma_f32_16x16x32_bf16 v[80:83], v[160:163], v[200:203], v[80:83]
	v_mfma_f32_16x16x32_bf16 v[72:75], v[144:147], v[208:211], v[72:75]
	v_mfma_f32_16x16x32_bf16 v[64:67], v[160:163], v[208:211], v[64:67]
	v_mfma_f32_16x16x32_bf16 v[116:119], v[156:159], v[188:191], v[116:119]
	v_mfma_f32_16x16x32_bf16 v[112:115], v[164:167], v[188:191], v[112:115]
	v_mfma_f32_16x16x32_bf16 v[100:103], v[156:159], v[196:199], v[100:103]
	v_mfma_f32_16x16x32_bf16 v[96:99], v[164:167], v[196:199], v[96:99]
	v_mfma_f32_16x16x32_bf16 v[84:87], v[156:159], v[204:207], v[84:87]
	v_mfma_f32_16x16x32_bf16 v[80:83], v[164:167], v[204:207], v[80:83]
	v_mfma_f32_16x16x32_bf16 v[72:75], v[156:159], v[212:215], v[72:75]
	v_mfma_f32_16x16x32_bf16 v[64:67], v[164:167], v[212:215], v[64:67]
	s_setprio 0
	s_setprio 1
	v_mfma_f32_16x16x32_bf16 v[124:127], v[168:171], v[184:187], v[124:127]
	v_mfma_f32_16x16x32_bf16 v[120:123], v[176:179], v[184:187], v[120:123]
	v_mfma_f32_16x16x32_bf16 v[108:111], v[168:171], v[192:195], v[108:111]
	v_mfma_f32_16x16x32_bf16 v[104:107], v[176:179], v[192:195], v[104:107]
	v_mfma_f32_16x16x32_bf16 v[92:95], v[168:171], v[200:203], v[92:95]
	v_mfma_f32_16x16x32_bf16 v[88:91], v[176:179], v[200:203], v[88:91]
	v_mfma_f32_16x16x32_bf16 v[76:79], v[168:171], v[208:211], v[76:79]
	v_mfma_f32_16x16x32_bf16 v[68:71], v[176:179], v[208:211], v[68:71]
	v_mfma_f32_16x16x32_bf16 v[124:127], v[172:175], v[188:191], v[124:127]
	v_mfma_f32_16x16x32_bf16 v[120:123], v[180:183], v[188:191], v[120:123]
	v_mfma_f32_16x16x32_bf16 v[108:111], v[172:175], v[196:199], v[108:111]
	v_mfma_f32_16x16x32_bf16 v[104:107], v[180:183], v[196:199], v[104:107]
	v_mfma_f32_16x16x32_bf16 v[92:95], v[172:175], v[204:207], v[92:95]
	v_mfma_f32_16x16x32_bf16 v[88:91], v[180:183], v[204:207], v[88:91]
	v_mfma_f32_16x16x32_bf16 v[76:79], v[172:175], v[212:215], v[76:79]
	v_mfma_f32_16x16x32_bf16 v[68:71], v[180:183], v[212:215], v[68:71]
	s_setprio 0
	s_barrier
	s_add_i32 s20, s47, s50
	v_lshl_add_u64 v[216:217], v[216:217], 0, s[12:13]
	s_mov_b32 m0, s20
	ds_read_b128 v[184:187], v153 offset:49152
	ds_read_b128 v[188:191], v153 offset:50176
	ds_read_b128 v[192:195], v153 offset:51200
	ds_read_b128 v[196:199], v153 offset:52224
	ds_read_b128 v[200:203], v153 offset:53248
	ds_read_b128 v[204:207], v153 offset:54272
	ds_read_b128 v[208:211], v153 offset:55296
	ds_read_b128 v[212:215], v153 offset:56320
	global_load_lds_dwordx4 v[216:217], off
	s_add_i32 m0, s20, 0x2000
	s_add_u32 s10, s10, 0x40080
	v_lshl_add_u64 v[216:217], v[218:219], 0, s[12:13]
	s_addc_u32 s11, s11, 0
	s_add_i32 s20, s48, s50
	global_load_lds_dwordx4 v[216:217], off
	v_lshl_add_u64 v[216:217], s[10:11], 0, v[132:133]
	s_mov_b32 m0, s20
	s_nop 0
	global_load_lds_dwordx4 v[216:217], off
	v_lshl_add_u64 v[216:217], s[10:11], 0, v[128:129]
	s_add_i32 m0, s20, 0x2000
	s_nop 0
	global_load_lds_dwordx4 v[216:217], off
	v_lshl_add_u64 v[216:217], v[220:221], 0, s[12:13]
	s_mov_b32 m0, s34
	s_nop 0
	global_load_lds_dwordx4 v[216:217], off
	v_lshl_add_u64 v[216:217], v[222:223], 0, s[12:13]
	s_mov_b32 m0, s35
	s_nop 0
	global_load_lds_dwordx4 v[216:217], off
	s_waitcnt vmcnt(8)
	s_waitcnt lgkmcnt(0)
	s_barrier
	s_setprio 1
	s_waitcnt lgkmcnt(0)
	v_mfma_f32_16x16x32_bf16 v[56:59], v[144:147], v[184:187], v[56:59]
	v_mfma_f32_16x16x32_bf16 v[48:51], v[160:163], v[184:187], v[48:51]
	v_mfma_f32_16x16x32_bf16 v[40:43], v[144:147], v[192:195], v[40:43]
	v_mfma_f32_16x16x32_bf16 v[32:35], v[160:163], v[192:195], v[32:35]
	v_mfma_f32_16x16x32_bf16 v[24:27], v[144:147], v[200:203], v[24:27]
	v_mfma_f32_16x16x32_bf16 v[16:19], v[160:163], v[200:203], v[16:19]
	v_mfma_f32_16x16x32_bf16 v[8:11], v[144:147], v[208:211], v[8:11]
	v_mfma_f32_16x16x32_bf16 v[0:3], v[160:163], v[208:211], v[0:3]
	v_mfma_f32_16x16x32_bf16 v[56:59], v[156:159], v[188:191], v[56:59]
	v_mfma_f32_16x16x32_bf16 v[48:51], v[164:167], v[188:191], v[48:51]
	v_mfma_f32_16x16x32_bf16 v[40:43], v[156:159], v[196:199], v[40:43]
	v_mfma_f32_16x16x32_bf16 v[32:35], v[164:167], v[196:199], v[32:35]
	v_mfma_f32_16x16x32_bf16 v[24:27], v[156:159], v[204:207], v[24:27]
	v_mfma_f32_16x16x32_bf16 v[16:19], v[164:167], v[204:207], v[16:19]
	v_mfma_f32_16x16x32_bf16 v[8:11], v[156:159], v[212:215], v[8:11]
	v_mfma_f32_16x16x32_bf16 v[0:3], v[164:167], v[212:215], v[0:3]
	s_setprio 0
	s_setprio 1
	v_mfma_f32_16x16x32_bf16 v[60:63], v[168:171], v[184:187], v[60:63]
	v_mfma_f32_16x16x32_bf16 v[52:55], v[176:179], v[184:187], v[52:55]
	v_mfma_f32_16x16x32_bf16 v[44:47], v[168:171], v[192:195], v[44:47]
	v_mfma_f32_16x16x32_bf16 v[36:39], v[176:179], v[192:195], v[36:39]
	v_mfma_f32_16x16x32_bf16 v[28:31], v[168:171], v[200:203], v[28:31]
	v_mfma_f32_16x16x32_bf16 v[20:23], v[176:179], v[200:203], v[20:23]
	v_mfma_f32_16x16x32_bf16 v[12:15], v[168:171], v[208:211], v[12:15]
	v_mfma_f32_16x16x32_bf16 v[4:7], v[176:179], v[208:211], v[4:7]
	v_mfma_f32_16x16x32_bf16 v[60:63], v[172:175], v[188:191], v[60:63]
	v_mfma_f32_16x16x32_bf16 v[52:55], v[180:183], v[188:191], v[52:55]
	v_mfma_f32_16x16x32_bf16 v[44:47], v[172:175], v[196:199], v[44:47]
	v_mfma_f32_16x16x32_bf16 v[36:39], v[180:183], v[196:199], v[36:39]
	v_mfma_f32_16x16x32_bf16 v[28:31], v[172:175], v[204:207], v[28:31]
	v_mfma_f32_16x16x32_bf16 v[20:23], v[180:183], v[204:207], v[20:23]
	v_mfma_f32_16x16x32_bf16 v[12:15], v[172:175], v[212:215], v[12:15]
	v_mfma_f32_16x16x32_bf16 v[4:7], v[180:183], v[212:215], v[4:7]
	s_setprio 0
	s_barrier
	s_add_i32 s46, s46, 2
	s_add_u32 s24, s24, 0x100
	s_addc_u32 s25, s25, 0
	s_add_u32 s44, s44, 0x100
	s_addc_u32 s45, s45, 0
	s_cmp_gt_u32 s46, 13

.Lh9_after:
	s_and_b64 vcc, exec, s[54:55]
	s_cbranch_vccz .LBB0_1006
	s_barrier
.LBB0_1006:
	v_lshl_add_u32 v144, s0, 8, v148
	s_bfe_u32 s99, s101, 0x10001
	s_lshl_b32 s99, s99, 7
	v_add_u32_e32 v144, s99, v144
	v_ashrrev_i32_e32 v145, 31, v144
	v_lshl_add_u64 v[146:147], v[144:145], 2, s[8:9]
	global_load_dword v170, v[146:147], off
	global_load_dword v171, v[146:147], off offset:64
	global_load_dword v172, v[146:147], off offset:128
	global_load_dword v173, v[146:147], off offset:192
	global_load_dword v174, v[146:147], off offset:512
	global_load_dword v175, v[146:147], off offset:576
	global_load_dword v176, v[146:147], off offset:640
	global_load_dword v177, v[146:147], off offset:704
	v_lshl_add_u32 v156, s1, 7, v150
	v_readlane_b32 s0, v255, 0
	v_readlane_b32 s1, v255, 1
	v_mul_lo_u32 v161, v144, s41
	v_mov_b32_e32 v158, 0xbfb8aa3b
	v_mov_b32_e32 v160, 1.0
	v_lshl_add_u32 v161, v156, 1, v161
	s_waitcnt vmcnt(0)
	v_fmamk_f32 v144, v170, 0x3a800000, v154
	v_mul_f32_e32 v145, 0x4b800000, v144
	v_cmp_gt_f32_e32 vcc, s40, v144
	s_nop 1
	v_cndmask_b32_e32 v144, v144, v145, vcc
	v_rsq_f32_e32 v144, v144
	s_nop 0
	v_mul_f32_e32 v145, 0x45800000, v144
	v_cndmask_b32_e32 v146, v144, v145, vcc
	v_pk_mul_f32 v[116:117], v[116:117], v[146:147] op_sel_hi:[1,0]
	v_pk_mul_f32 v[118:119], v[118:119], v[146:147] op_sel_hi:[1,0]
	v_pk_mul_f32 v[112:113], v[112:113], v[146:147] op_sel_hi:[1,0]
	v_pk_mul_f32 v[114:115], v[114:115], v[146:147] op_sel_hi:[1,0]
	v_pk_mul_f32 v[124:125], v[124:125], v[146:147] op_sel_hi:[1,0]
	v_pk_mul_f32 v[126:127], v[126:127], v[146:147] op_sel_hi:[1,0]
	v_pk_mul_f32 v[120:121], v[120:121], v[146:147] op_sel_hi:[1,0]
	v_pk_mul_f32 v[122:123], v[122:123], v[146:147] op_sel_hi:[1,0]
	v_pk_mul_f32 v[162:163], v[116:117], v[158:159] op_sel_hi:[1,0]
	v_pk_mul_f32 v[164:165], v[118:119], v[158:159] op_sel_hi:[1,0]
	v_pk_mul_f32 v[166:167], v[112:113], v[158:159] op_sel_hi:[1,0]
	v_pk_mul_f32 v[168:169], v[114:115], v[158:159] op_sel_hi:[1,0]
	v_exp_f32_e32 v162, v162
	v_exp_f32_e32 v163, v163
	v_exp_f32_e32 v164, v164
	v_exp_f32_e32 v165, v165
	v_exp_f32_e32 v166, v166
	v_exp_f32_e32 v167, v167
	v_exp_f32_e32 v168, v168
	v_exp_f32_e32 v169, v169
	v_pk_add_f32 v[162:163], v[162:163], v[160:161] op_sel_hi:[1,0]
	v_pk_add_f32 v[164:165], v[164:165], v[160:161] op_sel_hi:[1,0]
	v_pk_add_f32 v[166:167], v[166:167], v[160:161] op_sel_hi:[1,0]
	v_pk_add_f32 v[168:169], v[168:169], v[160:161] op_sel_hi:[1,0]
	v_rcp_f32_e32 v162, v162
	v_rcp_f32_e32 v163, v163
	v_rcp_f32_e32 v164, v164
	v_rcp_f32_e32 v165, v165
	v_rcp_f32_e32 v166, v166
	v_rcp_f32_e32 v167, v167
	v_rcp_f32_e32 v168, v168
	v_rcp_f32_e32 v169, v169
	v_pk_mul_f32 v[162:163], v[116:117], v[162:163]
	v_pk_mul_f32 v[164:165], v[118:119], v[164:165]
	v_pk_mul_f32 v[166:167], v[112:113], v[166:167]
	v_pk_mul_f32 v[168:169], v[114:115], v[168:169]
	v_pk_mul_f32 v[162:163], v[124:125], v[162:163]
	v_pk_mul_f32 v[164:165], v[126:127], v[164:165]
	v_pk_mul_f32 v[166:167], v[120:121], v[166:167]
	v_pk_mul_f32 v[168:169], v[122:123], v[168:169]
	v_cvt_pk_bf16_f32 v112, v162, v163
	v_cvt_pk_bf16_f32 v113, v164, v165
	v_cvt_pk_bf16_f32 v114, v166, v167
	v_cvt_pk_bf16_f32 v115, v168, v169
	global_store_dwordx4 v161, v[112:115], s[0:1]
	v_add_u32_e32 v161, 0x16000, v161
	v_fmamk_f32 v144, v171, 0x3a800000, v154
	v_mul_f32_e32 v145, 0x4b800000, v144
	v_cmp_gt_f32_e32 vcc, s40, v144
	s_nop 1
	v_cndmask_b32_e32 v144, v144, v145, vcc
	v_rsq_f32_e32 v144, v144
	s_nop 0
	v_mul_f32_e32 v145, 0x45800000, v144
	v_cndmask_b32_e32 v146, v144, v145, vcc
	v_pk_mul_f32 v[100:101], v[100:101], v[146:147] op_sel_hi:[1,0]
	v_pk_mul_f32 v[102:103], v[102:103], v[146:147] op_sel_hi:[1,0]
	v_pk_mul_f32 v[96:97], v[96:97], v[146:147] op_sel_hi:[1,0]
	v_pk_mul_f32 v[98:99], v[98:99], v[146:147] op_sel_hi:[1,0]
	v_pk_mul_f32 v[108:109], v[108:109], v[146:147] op_sel_hi:[1,0]
	v_pk_mul_f32 v[110:111], v[110:111], v[146:147] op_sel_hi:[1,0]
	v_pk_mul_f32 v[104:105], v[104:105], v[146:147] op_sel_hi:[1,0]
	v_pk_mul_f32 v[106:107], v[106:107], v[146:147] op_sel_hi:[1,0]
	v_pk_mul_f32 v[162:163], v[100:101], v[158:159] op_sel_hi:[1,0]
	v_pk_mul_f32 v[164:165], v[102:103], v[158:159] op_sel_hi:[1,0]
	v_pk_mul_f32 v[166:167], v[96:97], v[158:159] op_sel_hi:[1,0]
	v_pk_mul_f32 v[168:169], v[98:99], v[158:159] op_sel_hi:[1,0]
	v_exp_f32_e32 v162, v162
	v_exp_f32_e32 v163, v163
	v_exp_f32_e32 v164, v164
	v_exp_f32_e32 v165, v165
	v_exp_f32_e32 v166, v166
	v_exp_f32_e32 v167, v167
	v_exp_f32_e32 v168, v168
	v_exp_f32_e32 v169, v169
	v_pk_add_f32 v[162:163], v[162:163], v[160:161] op_sel_hi:[1,0]
	v_pk_add_f32 v[164:165], v[164:165], v[160:161] op_sel_hi:[1,0]
	v_pk_add_f32 v[166:167], v[166:167], v[160:161] op_sel_hi:[1,0]
	v_pk_add_f32 v[168:169], v[168:169], v[160:161] op_sel_hi:[1,0]
	v_rcp_f32_e32 v162, v162
	v_rcp_f32_e32 v163, v163
	v_rcp_f32_e32 v164, v164
	v_rcp_f32_e32 v165, v165
	v_rcp_f32_e32 v166, v166
	v_rcp_f32_e32 v167, v167
	v_rcp_f32_e32 v168, v168
	v_rcp_f32_e32 v169, v169
	v_pk_mul_f32 v[162:163], v[100:101], v[162:163]
	v_pk_mul_f32 v[164:165], v[102:103], v[164:165]
	v_pk_mul_f32 v[166:167], v[96:97], v[166:167]
	v_pk_mul_f32 v[168:169], v[98:99], v[168:169]
	v_pk_mul_f32 v[162:163], v[108:109], v[162:163]
	v_pk_mul_f32 v[164:165], v[110:111], v[164:165]
	v_pk_mul_f32 v[166:167], v[104:105], v[166:167]
	v_pk_mul_f32 v[168:169], v[106:107], v[168:169]
	v_cvt_pk_bf16_f32 v96, v162, v163
	v_cvt_pk_bf16_f32 v97, v164, v165
	v_cvt_pk_bf16_f32 v98, v166, v167
	v_cvt_pk_bf16_f32 v99, v168, v169
	global_store_dwordx4 v161, v[96:99], s[0:1]
	v_add_u32_e32 v161, 0x16000, v161
	v_fmamk_f32 v144, v172, 0x3a800000, v154
	v_mul_f32_e32 v145, 0x4b800000, v144
	v_cmp_gt_f32_e32 vcc, s40, v144
	s_nop 1
	v_cndmask_b32_e32 v144, v144, v145, vcc
	v_rsq_f32_e32 v144, v144
	s_nop 0
	v_mul_f32_e32 v145, 0x45800000, v144
	v_cndmask_b32_e32 v146, v144, v145, vcc
	v_pk_mul_f32 v[84:85], v[84:85], v[146:147] op_sel_hi:[1,0]
	v_pk_mul_f32 v[86:87], v[86:87], v[146:147] op_sel_hi:[1,0]
	v_pk_mul_f32 v[80:81], v[80:81], v[146:147] op_sel_hi:[1,0]
	v_pk_mul_f32 v[82:83], v[82:83], v[146:147] op_sel_hi:[1,0]
	v_pk_mul_f32 v[92:93], v[92:93], v[146:147] op_sel_hi:[1,0]
	v_pk_mul_f32 v[94:95], v[94:95], v[146:147] op_sel_hi:[1,0]
	v_pk_mul_f32 v[88:89], v[88:89], v[146:147] op_sel_hi:[1,0]
	v_pk_mul_f32 v[90:91], v[90:91], v[146:147] op_sel_hi:[1,0]
	v_pk_mul_f32 v[162:163], v[84:85], v[158:159] op_sel_hi:[1,0]
	v_pk_mul_f32 v[164:165], v[86:87], v[158:159] op_sel_hi:[1,0]
	v_pk_mul_f32 v[166:167], v[80:81], v[158:159] op_sel_hi:[1,0]
	v_pk_mul_f32 v[168:169], v[82:83], v[158:159] op_sel_hi:[1,0]
	v_exp_f32_e32 v162, v162
	v_exp_f32_e32 v163, v163
	v_exp_f32_e32 v164, v164
	v_exp_f32_e32 v165, v165
	v_exp_f32_e32 v166, v166
	v_exp_f32_e32 v167, v167
	v_exp_f32_e32 v168, v168
	v_exp_f32_e32 v169, v169
	v_pk_add_f32 v[162:163], v[162:163], v[160:161] op_sel_hi:[1,0]
	v_pk_add_f32 v[164:165], v[164:165], v[160:161] op_sel_hi:[1,0]
	v_pk_add_f32 v[166:167], v[166:167], v[160:161] op_sel_hi:[1,0]
	v_pk_add_f32 v[168:169], v[168:169], v[160:161] op_sel_hi:[1,0]
	v_rcp_f32_e32 v162, v162
	v_rcp_f32_e32 v163, v163
	v_rcp_f32_e32 v164, v164
	v_rcp_f32_e32 v165, v165
	v_rcp_f32_e32 v166, v166
	v_rcp_f32_e32 v167, v167
	v_rcp_f32_e32 v168, v168
	v_rcp_f32_e32 v169, v169
	v_pk_mul_f32 v[162:163], v[84:85], v[162:163]
	v_pk_mul_f32 v[164:165], v[86:87], v[164:165]
	v_pk_mul_f32 v[166:167], v[80:81], v[166:167]
	v_pk_mul_f32 v[168:169], v[82:83], v[168:169]
	v_pk_mul_f32 v[162:163], v[92:93], v[162:163]
	v_pk_mul_f32 v[164:165], v[94:95], v[164:165]
	v_pk_mul_f32 v[166:167], v[88:89], v[166:167]
	v_pk_mul_f32 v[168:169], v[90:91], v[168:169]
	v_cvt_pk_bf16_f32 v80, v162, v163
	v_cvt_pk_bf16_f32 v81, v164, v165
	v_cvt_pk_bf16_f32 v82, v166, v167
	v_cvt_pk_bf16_f32 v83, v168, v169
	global_store_dwordx4 v161, v[80:83], s[0:1]
	v_add_u32_e32 v161, 0x16000, v161
	v_fmamk_f32 v144, v173, 0x3a800000, v154
	v_mul_f32_e32 v145, 0x4b800000, v144
	v_cmp_gt_f32_e32 vcc, s40, v144
	s_nop 1
	v_cndmask_b32_e32 v144, v144, v145, vcc
	v_rsq_f32_e32 v144, v144
	s_nop 0
	v_mul_f32_e32 v145, 0x45800000, v144
	v_cndmask_b32_e32 v146, v144, v145, vcc
	v_pk_mul_f32 v[72:73], v[72:73], v[146:147] op_sel_hi:[1,0]
	v_pk_mul_f32 v[74:75], v[74:75], v[146:147] op_sel_hi:[1,0]
	v_pk_mul_f32 v[64:65], v[64:65], v[146:147] op_sel_hi:[1,0]
	v_pk_mul_f32 v[66:67], v[66:67], v[146:147] op_sel_hi:[1,0]
	v_pk_mul_f32 v[76:77], v[76:77], v[146:147] op_sel_hi:[1,0]
	v_pk_mul_f32 v[78:79], v[78:79], v[146:147] op_sel_hi:[1,0]
	v_pk_mul_f32 v[68:69], v[68:69], v[146:147] op_sel_hi:[1,0]
	v_pk_mul_f32 v[70:71], v[70:71], v[146:147] op_sel_hi:[1,0]
	v_pk_mul_f32 v[162:163], v[72:73], v[158:159] op_sel_hi:[1,0]
	v_pk_mul_f32 v[164:165], v[74:75], v[158:159] op_sel_hi:[1,0]
	v_pk_mul_f32 v[166:167], v[64:65], v[158:159] op_sel_hi:[1,0]
	v_pk_mul_f32 v[168:169], v[66:67], v[158:159] op_sel_hi:[1,0]
	v_exp_f32_e32 v162, v162
	v_exp_f32_e32 v163, v163
	v_exp_f32_e32 v164, v164
	v_exp_f32_e32 v165, v165
	v_exp_f32_e32 v166, v166
	v_exp_f32_e32 v167, v167
	v_exp_f32_e32 v168, v168
	v_exp_f32_e32 v169, v169
	v_pk_add_f32 v[162:163], v[162:163], v[160:161] op_sel_hi:[1,0]
	v_pk_add_f32 v[164:165], v[164:165], v[160:161] op_sel_hi:[1,0]
	v_pk_add_f32 v[166:167], v[166:167], v[160:161] op_sel_hi:[1,0]
	v_pk_add_f32 v[168:169], v[168:169], v[160:161] op_sel_hi:[1,0]
	v_rcp_f32_e32 v162, v162
	v_rcp_f32_e32 v163, v163
	v_rcp_f32_e32 v164, v164
	v_rcp_f32_e32 v165, v165
	v_rcp_f32_e32 v166, v166
	v_rcp_f32_e32 v167, v167
	v_rcp_f32_e32 v168, v168
	v_rcp_f32_e32 v169, v169
	v_pk_mul_f32 v[162:163], v[72:73], v[162:163]
	v_pk_mul_f32 v[164:165], v[74:75], v[164:165]
	v_pk_mul_f32 v[166:167], v[64:65], v[166:167]
	v_pk_mul_f32 v[168:169], v[66:67], v[168:169]
	v_pk_mul_f32 v[162:163], v[76:77], v[162:163]
	v_pk_mul_f32 v[164:165], v[78:79], v[164:165]
	v_pk_mul_f32 v[166:167], v[68:69], v[166:167]
	v_pk_mul_f32 v[168:169], v[70:71], v[168:169]
	v_cvt_pk_bf16_f32 v64, v162, v163
	v_cvt_pk_bf16_f32 v65, v164, v165
	v_cvt_pk_bf16_f32 v66, v166, v167
	v_cvt_pk_bf16_f32 v67, v168, v169
	global_store_dwordx4 v161, v[64:67], s[0:1]
	v_add_u32_e32 v161, 0x6e000, v161
	s_bitcmp1_b32 s101, 0
	s_cbranch_scc1 .Lh9_epi_end
	v_fmamk_f32 v144, v174, 0x3a800000, v154
	v_mul_f32_e32 v145, 0x4b800000, v144
	v_cmp_gt_f32_e32 vcc, s40, v144
	s_nop 1
	v_cndmask_b32_e32 v144, v144, v145, vcc
	v_rsq_f32_e32 v144, v144
	s_nop 0
	v_mul_f32_e32 v145, 0x45800000, v144
	v_cndmask_b32_e32 v146, v144, v145, vcc
	v_pk_mul_f32 v[56:57], v[56:57], v[146:147] op_sel_hi:[1,0]
	v_pk_mul_f32 v[58:59], v[58:59], v[146:147] op_sel_hi:[1,0]
	v_pk_mul_f32 v[48:49], v[48:49], v[146:147] op_sel_hi:[1,0]
	v_pk_mul_f32 v[50:51], v[50:51], v[146:147] op_sel_hi:[1,0]
	v_pk_mul_f32 v[60:61], v[60:61], v[146:147] op_sel_hi:[1,0]
	v_pk_mul_f32 v[62:63], v[62:63], v[146:147] op_sel_hi:[1,0]
	v_pk_mul_f32 v[52:53], v[52:53], v[146:147] op_sel_hi:[1,0]
	v_pk_mul_f32 v[54:55], v[54:55], v[146:147] op_sel_hi:[1,0]
	v_pk_mul_f32 v[162:163], v[56:57], v[158:159] op_sel_hi:[1,0]
	v_pk_mul_f32 v[164:165], v[58:59], v[158:159] op_sel_hi:[1,0]
	v_pk_mul_f32 v[166:167], v[48:49], v[158:159] op_sel_hi:[1,0]
	v_pk_mul_f32 v[168:169], v[50:51], v[158:159] op_sel_hi:[1,0]
	v_exp_f32_e32 v162, v162
	v_exp_f32_e32 v163, v163
	v_exp_f32_e32 v164, v164
	v_exp_f32_e32 v165, v165
	v_exp_f32_e32 v166, v166
	v_exp_f32_e32 v167, v167
	v_exp_f32_e32 v168, v168
	v_exp_f32_e32 v169, v169
	v_pk_add_f32 v[162:163], v[162:163], v[160:161] op_sel_hi:[1,0]
	v_pk_add_f32 v[164:165], v[164:165], v[160:161] op_sel_hi:[1,0]
	v_pk_add_f32 v[166:167], v[166:167], v[160:161] op_sel_hi:[1,0]
	v_pk_add_f32 v[168:169], v[168:169], v[160:161] op_sel_hi:[1,0]
	v_rcp_f32_e32 v162, v162
	v_rcp_f32_e32 v163, v163
	v_rcp_f32_e32 v164, v164
	v_rcp_f32_e32 v165, v165
	v_rcp_f32_e32 v166, v166
	v_rcp_f32_e32 v167, v167
	v_rcp_f32_e32 v168, v168
	v_rcp_f32_e32 v169, v169
	v_pk_mul_f32 v[162:163], v[56:57], v[162:163]
	v_pk_mul_f32 v[164:165], v[58:59], v[164:165]
	v_pk_mul_f32 v[166:167], v[48:49], v[166:167]
	v_pk_mul_f32 v[168:169], v[50:51], v[168:169]
	v_pk_mul_f32 v[162:163], v[60:61], v[162:163]
	v_pk_mul_f32 v[164:165], v[62:63], v[164:165]
	v_pk_mul_f32 v[166:167], v[52:53], v[166:167]
	v_pk_mul_f32 v[168:169], v[54:55], v[168:169]
	v_cvt_pk_bf16_f32 v48, v162, v163
	v_cvt_pk_bf16_f32 v49, v164, v165
	v_cvt_pk_bf16_f32 v50, v166, v167
	v_cvt_pk_bf16_f32 v51, v168, v169
	global_store_dwordx4 v161, v[48:51], s[0:1]
	v_add_u32_e32 v161, 0x16000, v161
	v_fmamk_f32 v144, v175, 0x3a800000, v154
	v_mul_f32_e32 v145, 0x4b800000, v144
	v_cmp_gt_f32_e32 vcc, s40, v144
	s_nop 1
	v_cndmask_b32_e32 v144, v144, v145, vcc
	v_rsq_f32_e32 v144, v144
	s_nop 0
	v_mul_f32_e32 v145, 0x45800000, v144
	v_cndmask_b32_e32 v146, v144, v145, vcc
	v_pk_mul_f32 v[40:41], v[40:41], v[146:147] op_sel_hi:[1,0]
	v_pk_mul_f32 v[42:43], v[42:43], v[146:147] op_sel_hi:[1,0]
	v_pk_mul_f32 v[32:33], v[32:33], v[146:147] op_sel_hi:[1,0]
	v_pk_mul_f32 v[34:35], v[34:35], v[146:147] op_sel_hi:[1,0]
	v_pk_mul_f32 v[44:45], v[44:45], v[146:147] op_sel_hi:[1,0]
	v_pk_mul_f32 v[46:47], v[46:47], v[146:147] op_sel_hi:[1,0]
	v_pk_mul_f32 v[36:37], v[36:37], v[146:147] op_sel_hi:[1,0]
	v_pk_mul_f32 v[38:39], v[38:39], v[146:147] op_sel_hi:[1,0]
	v_pk_mul_f32 v[162:163], v[40:41], v[158:159] op_sel_hi:[1,0]
	v_pk_mul_f32 v[164:165], v[42:43], v[158:159] op_sel_hi:[1,0]
	v_pk_mul_f32 v[166:167], v[32:33], v[158:159] op_sel_hi:[1,0]
	v_pk_mul_f32 v[168:169], v[34:35], v[158:159] op_sel_hi:[1,0]
	v_exp_f32_e32 v162, v162
	v_exp_f32_e32 v163, v163
	v_exp_f32_e32 v164, v164
	v_exp_f32_e32 v165, v165
	v_exp_f32_e32 v166, v166
	v_exp_f32_e32 v167, v167
	v_exp_f32_e32 v168, v168
	v_exp_f32_e32 v169, v169
	v_pk_add_f32 v[162:163], v[162:163], v[160:161] op_sel_hi:[1,0]
	v_pk_add_f32 v[164:165], v[164:165], v[160:161] op_sel_hi:[1,0]
	v_pk_add_f32 v[166:167], v[166:167], v[160:161] op_sel_hi:[1,0]
	v_pk_add_f32 v[168:169], v[168:169], v[160:161] op_sel_hi:[1,0]
	v_rcp_f32_e32 v162, v162
	v_rcp_f32_e32 v163, v163
	v_rcp_f32_e32 v164, v164
	v_rcp_f32_e32 v165, v165
	v_rcp_f32_e32 v166, v166
	v_rcp_f32_e32 v167, v167
	v_rcp_f32_e32 v168, v168
	v_rcp_f32_e32 v169, v169
	v_pk_mul_f32 v[162:163], v[40:41], v[162:163]
	v_pk_mul_f32 v[164:165], v[42:43], v[164:165]
	v_pk_mul_f32 v[166:167], v[32:33], v[166:167]
	v_pk_mul_f32 v[168:169], v[34:35], v[168:169]
	v_pk_mul_f32 v[162:163], v[44:45], v[162:163]
	v_pk_mul_f32 v[164:165], v[46:47], v[164:165]
	v_pk_mul_f32 v[166:167], v[36:37], v[166:167]
	v_pk_mul_f32 v[168:169], v[38:39], v[168:169]
	v_cvt_pk_bf16_f32 v32, v162, v163
	v_cvt_pk_bf16_f32 v33, v164, v165
	v_cvt_pk_bf16_f32 v34, v166, v167
	v_cvt_pk_bf16_f32 v35, v168, v169
	global_store_dwordx4 v161, v[32:35], s[0:1]
	v_add_u32_e32 v161, 0x16000, v161
	v_fmamk_f32 v144, v176, 0x3a800000, v154
	v_mul_f32_e32 v145, 0x4b800000, v144
	v_cmp_gt_f32_e32 vcc, s40, v144
	s_nop 1
	v_cndmask_b32_e32 v144, v144, v145, vcc
	v_rsq_f32_e32 v144, v144
	s_nop 0
	v_mul_f32_e32 v145, 0x45800000, v144
	v_cndmask_b32_e32 v146, v144, v145, vcc
	v_pk_mul_f32 v[24:25], v[24:25], v[146:147] op_sel_hi:[1,0]
	v_pk_mul_f32 v[26:27], v[26:27], v[146:147] op_sel_hi:[1,0]
	v_pk_mul_f32 v[16:17], v[16:17], v[146:147] op_sel_hi:[1,0]
	v_pk_mul_f32 v[18:19], v[18:19], v[146:147] op_sel_hi:[1,0]
	v_pk_mul_f32 v[28:29], v[28:29], v[146:147] op_sel_hi:[1,0]
	v_pk_mul_f32 v[30:31], v[30:31], v[146:147] op_sel_hi:[1,0]
	v_pk_mul_f32 v[20:21], v[20:21], v[146:147] op_sel_hi:[1,0]
	v_pk_mul_f32 v[22:23], v[22:23], v[146:147] op_sel_hi:[1,0]
	v_pk_mul_f32 v[162:163], v[24:25], v[158:159] op_sel_hi:[1,0]
	v_pk_mul_f32 v[164:165], v[26:27], v[158:159] op_sel_hi:[1,0]
	v_pk_mul_f32 v[166:167], v[16:17], v[158:159] op_sel_hi:[1,0]
	v_pk_mul_f32 v[168:169], v[18:19], v[158:159] op_sel_hi:[1,0]
	v_exp_f32_e32 v162, v162
	v_exp_f32_e32 v163, v163
	v_exp_f32_e32 v164, v164
	v_exp_f32_e32 v165, v165
	v_exp_f32_e32 v166, v166
	v_exp_f32_e32 v167, v167
	v_exp_f32_e32 v168, v168
	v_exp_f32_e32 v169, v169
	v_pk_add_f32 v[162:163], v[162:163], v[160:161] op_sel_hi:[1,0]
	v_pk_add_f32 v[164:165], v[164:165], v[160:161] op_sel_hi:[1,0]
	v_pk_add_f32 v[166:167], v[166:167], v[160:161] op_sel_hi:[1,0]
	v_pk_add_f32 v[168:169], v[168:169], v[160:161] op_sel_hi:[1,0]
	v_rcp_f32_e32 v162, v162
	v_rcp_f32_e32 v163, v163
	v_rcp_f32_e32 v164, v164
	v_rcp_f32_e32 v165, v165
	v_rcp_f32_e32 v166, v166
	v_rcp_f32_e32 v167, v167
	v_rcp_f32_e32 v168, v168
	v_rcp_f32_e32 v169, v169
	v_pk_mul_f32 v[162:163], v[24:25], v[162:163]
	v_pk_mul_f32 v[164:165], v[26:27], v[164:165]
	v_pk_mul_f32 v[166:167], v[16:17], v[166:167]
	v_pk_mul_f32 v[168:169], v[18:19], v[168:169]
	v_pk_mul_f32 v[162:163], v[28:29], v[162:163]
	v_pk_mul_f32 v[164:165], v[30:31], v[164:165]
	v_pk_mul_f32 v[166:167], v[20:21], v[166:167]
	v_pk_mul_f32 v[168:169], v[22:23], v[168:169]
	v_cvt_pk_bf16_f32 v16, v162, v163
	v_cvt_pk_bf16_f32 v17, v164, v165
	v_cvt_pk_bf16_f32 v18, v166, v167
	v_cvt_pk_bf16_f32 v19, v168, v169
	global_store_dwordx4 v161, v[16:19], s[0:1]
	v_add_u32_e32 v161, 0x16000, v161
	v_fmamk_f32 v144, v177, 0x3a800000, v154
	v_mul_f32_e32 v145, 0x4b800000, v144
	v_cmp_gt_f32_e32 vcc, s40, v144
	s_nop 1
	v_cndmask_b32_e32 v144, v144, v145, vcc
	v_rsq_f32_e32 v144, v144
	s_nop 0
	v_mul_f32_e32 v145, 0x45800000, v144
	v_cndmask_b32_e32 v146, v144, v145, vcc
	v_pk_mul_f32 v[8:9], v[8:9], v[146:147] op_sel_hi:[1,0]
	v_pk_mul_f32 v[10:11], v[10:11], v[146:147] op_sel_hi:[1,0]
	v_pk_mul_f32 v[0:1], v[0:1], v[146:147] op_sel_hi:[1,0]
	v_pk_mul_f32 v[2:3], v[2:3], v[146:147] op_sel_hi:[1,0]
	v_pk_mul_f32 v[12:13], v[12:13], v[146:147] op_sel_hi:[1,0]
	v_pk_mul_f32 v[14:15], v[14:15], v[146:147] op_sel_hi:[1,0]
	v_pk_mul_f32 v[4:5], v[4:5], v[146:147] op_sel_hi:[1,0]
	v_pk_mul_f32 v[6:7], v[6:7], v[146:147] op_sel_hi:[1,0]
	v_pk_mul_f32 v[162:163], v[8:9], v[158:159] op_sel_hi:[1,0]
	v_pk_mul_f32 v[164:165], v[10:11], v[158:159] op_sel_hi:[1,0]
	v_pk_mul_f32 v[166:167], v[0:1], v[158:159] op_sel_hi:[1,0]
	v_pk_mul_f32 v[168:169], v[2:3], v[158:159] op_sel_hi:[1,0]
	v_exp_f32_e32 v162, v162
	v_exp_f32_e32 v163, v163
	v_exp_f32_e32 v164, v164
	v_exp_f32_e32 v165, v165
	v_exp_f32_e32 v166, v166
	v_exp_f32_e32 v167, v167
	v_exp_f32_e32 v168, v168
	v_exp_f32_e32 v169, v169
	v_pk_add_f32 v[162:163], v[162:163], v[160:161] op_sel_hi:[1,0]
	v_pk_add_f32 v[164:165], v[164:165], v[160:161] op_sel_hi:[1,0]
	v_pk_add_f32 v[166:167], v[166:167], v[160:161] op_sel_hi:[1,0]
	v_pk_add_f32 v[168:169], v[168:169], v[160:161] op_sel_hi:[1,0]
	v_rcp_f32_e32 v162, v162
	v_rcp_f32_e32 v163, v163
	v_rcp_f32_e32 v164, v164
	v_rcp_f32_e32 v165, v165
	v_rcp_f32_e32 v166, v166
	v_rcp_f32_e32 v167, v167
	v_rcp_f32_e32 v168, v168
	v_rcp_f32_e32 v169, v169
	v_pk_mul_f32 v[162:163], v[8:9], v[162:163]
	v_pk_mul_f32 v[164:165], v[10:11], v[164:165]
	v_pk_mul_f32 v[166:167], v[0:1], v[166:167]
	v_pk_mul_f32 v[168:169], v[2:3], v[168:169]
	v_pk_mul_f32 v[162:163], v[12:13], v[162:163]
	v_pk_mul_f32 v[164:165], v[14:15], v[164:165]
	v_pk_mul_f32 v[166:167], v[4:5], v[166:167]
	v_pk_mul_f32 v[168:169], v[6:7], v[168:169]
	v_cvt_pk_bf16_f32 v0, v162, v163
	v_cvt_pk_bf16_f32 v1, v164, v165
	v_cvt_pk_bf16_f32 v2, v166, v167
	v_cvt_pk_bf16_f32 v3, v168, v169
	global_store_dwordx4 v161, v[0:3], s[0:1]
.Lh9_epi_end:
	s_andn2_b64 vcc, exec, s[4:5]
	s_mov_b64 s[0:1], -1
	s_cbranch_vccnz .LBB0_999
	s_andn2_b64 vcc, exec, s[6:7]
	s_cbranch_vccnz .LBB0_998
	s_barrier
	s_branch .LBB0_998
